# st7 + P3 first row group requested in the P2->P3 sync fast path before polling
# speedup vs baseline: 1.0048x; 1.0048x over previous
.LBB0_230:
	s_cmp_eq_u32 s58, 0x100
	s_cbranch_scc0 .Lb3_generic
	s_waitcnt vmcnt(0)
	s_barrier
	v_lshlrev_b32_e32 v168, 5, v0
	v_readlane_b32 s6, v244, 4
	v_readlane_b32 s7, v244, 5
	v_and_b32_e32 v168, 0x7e0, v168
	s_nop 4
	global_load_dwordx4 v[160:163], v168, s[6:7] offset:16
	global_load_dwordx4 v[164:167], v168, s[6:7]
	s_and_b32 s6, s57, 7
	s_lshl_b32 s6, s6, 12
	s_ashr_i32 s7, s57, 3
	s_lshl_b32 s7, s7, 7
	s_add_i32 s6, s6, s7
	s_ashr_i32 s7, s6, 31
	s_movk_i32 s13, 0x1200
	s_mov_b64 s[10:11], 0x1000
	s_mov_b64 s[16:17], 0x2000
	s_mov_b64 s[18:19], 0x4800
	s_mov_b64 s[24:25], 0x11de0000
	s_mov_b64 s[26:27], 0x13de0000
	s_mov_b64 s[28:29], 0xdde0000
	s_mov_b64 s[30:31], 0xdde1000
	s_mov_b64 s[32:33], 0x4be0000
	s_mov_b64 s[34:35], 0x4be1000
	s_mov_b64 s[36:37], 0x4be2000
	s_mov_b64 s[38:39], 0x4be3000
	v_lshrrev_b32_e32 v46, 2, v0
	v_and_b32_e32 v48, 63, v0
	v_and_b32_e32 v46, -16, v46
	v_mov_b32_e32 v47, 0
	v_lshlrev_b32_e32 v48, 4, v48
	v_mov_b32_e32 v49, 0
	v_lshl_add_u64 v[44:45], v[46:47], 0, s[6:7]
	v_mov_b64_e32 v[42:43], s[62:63]
	v_lshlrev_b64 v[38:39], 11, v[44:45]
	v_lshlrev_b64 v[40:41], 10, v[44:45]
	v_mad_u64_u32 v[42:43], s[0:1], v44, s13, v[42:43]
	v_lshl_add_u64 v[38:39], s[62:63], 0, v[38:39]
	v_lshl_add_u64 v[40:41], s[62:63], 0, v[40:41]
	v_mad_i32_i24 v43, v45, s13, v43
	v_lshl_add_u64 v[96:97], v[40:41], 0, v[48:49]
	v_lshl_add_u64 v[98:99], v[42:43], 0, v[48:49]
	v_lshl_add_u64 v[50:51], v[38:39], 0, v[48:49]
	v_lshl_add_u64 v[100:101], v[96:97], 0, s[24:25]
	v_lshl_add_u64 v[102:103], v[96:97], 0, s[26:27]
	global_load_dwordx4 v[54:57], v[100:101], off nt
	global_load_dwordx4 v[58:61], v[100:101], off offset:1024 nt
	global_load_dwordx4 v[62:65], v[100:101], off offset:2048 nt
	global_load_dwordx4 v[66:69], v[100:101], off offset:3072 nt
	global_load_dwordx4 v[70:73], v[102:103], off nt
	global_load_dwordx4 v[74:77], v[102:103], off offset:1024 nt
	global_load_dwordx4 v[78:81], v[102:103], off offset:2048 nt
	global_load_dwordx4 v[82:85], v[102:103], off offset:3072 nt
	v_lshl_add_u64 v[104:105], v[98:99], 0, s[32:33]
	v_lshl_add_u64 v[106:107], v[98:99], 0, s[34:35]
	v_lshl_add_u64 v[96:97], v[98:99], 0, s[36:37]
	v_lshl_add_u64 v[98:99], v[98:99], 0, s[38:39]
	global_load_dwordx4 v[88:91], v[104:105], off offset:1024 nt
	global_load_dwordx4 v[92:95], v[106:107], off offset:1536 nt
	global_load_dwordx4 v[114:117], v[96:97], off offset:2048 nt
	global_load_dwordx4 v[154:157], v[98:99], off offset:2560 nt
	v_lshl_add_u64 v[52:53], v[50:51], 0, s[28:29]
	v_lshl_add_u64 v[50:51], v[50:51], 0, s[30:31]
	v_lshl_add_u64 v[38:39], v[38:39], 0, s[16:17]
	v_lshl_add_u64 v[40:41], v[40:41], 0, s[10:11]
	v_lshl_add_u64 v[42:43], v[42:43], 0, s[18:19]
	s_mov_b64 s[0:1], exec
	v_readlane_b32 s4, v244, 8
	v_readlane_b32 s5, v244, 9
	s_and_b64 s[4:5], s[0:1], s[4:5]
	s_mov_b64 exec, s[4:5]
	s_cbranch_execz .LBB0_282
	s_and_b32 s2, s57, 7
	s_lshl_b32 s2, s2, 8
	s_add_u32 s2, s2, 0x3600
	v_mov_b32_e32 v2, s2
	v_mov_b32_e32 v3, 1
	s_mov_b32 s3, 0
	global_atomic_add v2, v3, s[52:53]

.LBB0_284:
	s_cmp_eq_u32 s58, 0x100
	s_cbranch_scc1 .Lp3_pf_done
	s_and_b32 s0, s22, 7
	s_lshl_b32 s0, s0, 12
	s_ashr_i32 s1, s23, 3
	s_lshl_b32 s1, s1, 7
	s_add_i32 s0, s0, s1
	s_ashr_i32 s1, s0, 31
	v_lshl_add_u64 v[44:45], v[20:21], 0, s[0:1]
	v_mov_b64_e32 v[42:43], s[62:63]
	v_lshlrev_b64 v[38:39], 11, v[44:45]
	v_lshlrev_b64 v[40:41], 10, v[44:45]
	v_mad_u64_u32 v[42:43], s[0:1], v44, s13, v[42:43]
	v_lshl_add_u64 v[38:39], s[62:63], 0, v[38:39]
	v_lshl_add_u64 v[40:41], s[62:63], 0, v[40:41]
	v_mad_i32_i24 v43, v45, s13, v43
	v_lshl_add_u64 v[96:97], v[40:41], 0, v[18:19]
	v_lshl_add_u64 v[98:99], v[42:43], 0, v[18:19]
	v_lshl_add_u64 v[50:51], v[38:39], 0, v[18:19]
	v_lshl_add_u64 v[100:101], v[96:97], 0, s[24:25]
	v_lshl_add_u64 v[102:103], v[96:97], 0, s[26:27]
	global_load_dwordx4 v[54:57], v[100:101], off nt
	global_load_dwordx4 v[58:61], v[100:101], off offset:1024 nt
	global_load_dwordx4 v[62:65], v[100:101], off offset:2048 nt
	global_load_dwordx4 v[66:69], v[100:101], off offset:3072 nt
	global_load_dwordx4 v[70:73], v[102:103], off nt
	global_load_dwordx4 v[74:77], v[102:103], off offset:1024 nt
	global_load_dwordx4 v[78:81], v[102:103], off offset:2048 nt
	global_load_dwordx4 v[82:85], v[102:103], off offset:3072 nt
	v_lshl_add_u64 v[104:105], v[98:99], 0, s[32:33]
	v_lshl_add_u64 v[106:107], v[98:99], 0, s[34:35]
	v_lshl_add_u64 v[96:97], v[98:99], 0, s[36:37]
	v_lshl_add_u64 v[98:99], v[98:99], 0, s[38:39]
	global_load_dwordx4 v[88:91], v[104:105], off offset:1024 nt
	global_load_dwordx4 v[92:95], v[106:107], off offset:1536 nt
	global_load_dwordx4 v[114:117], v[96:97], off offset:2048 nt
	global_load_dwordx4 v[154:157], v[98:99], off offset:2560 nt
	v_lshl_add_u64 v[52:53], v[50:51], 0, s[28:29]
	v_lshl_add_u64 v[50:51], v[50:51], 0, s[30:31]
	v_lshl_add_u64 v[38:39], v[38:39], 0, s[16:17]
	v_lshl_add_u64 v[40:41], v[40:41], 0, s[10:11]
	v_lshl_add_u64 v[42:43], v[42:43], 0, s[18:19]
